# sa + S5 carry scan loop: the 8 LDS reads of an unrolled block issued together (fresh registers, counted lgkmcnt waits)
# speedup vs baseline: 1.0092x; 1.0003x over previous
.LBB0_456:
	ds_read_b32 v24, v10
	ds_read_b32 v25, v10 offset:288
	ds_read_b32 v26, v10 offset:576
	ds_read_b32 v27, v10 offset:864
	ds_read_b32 v28, v10 offset:1152
	ds_read_b32 v29, v10 offset:1440
	ds_read_b32 v30, v10 offset:1728
	ds_read_b32 v31, v10 offset:2016
	v_cvt_pk_bf16_f32 v11, v8, v9
	v_pk_mul_f32 v[14:15], v[6:7], v[8:9] op_sel:[0,1]
	v_pk_fma_f32 v[18:19], v[2:3], v[8:9], v[14:15] neg_lo:[0,0,1] neg_hi:[0,0,1]
	v_pk_fma_f32 v[8:9], v[2:3], v[8:9], v[14:15] op_sel_hi:[1,0,1]
	v_lshl_add_u64 v[12:13], v[4:5], 0, s[6:7]
	v_mov_b32_e32 v19, v9
	s_waitcnt lgkmcnt(7)
	v_lshlrev_b32_e32 v8, 16, v24
	v_and_b32_e32 v9, 0xffff0000, v24
	v_add_co_u32_e32 v16, vcc, 0x6800000, v12
	v_pk_add_f32 v[8:9], v[18:19], v[8:9]
	v_add_co_u32_e64 v14, s[2:3], s8, v12
	v_addc_co_u32_e32 v17, vcc, 0, v13, vcc
	v_pk_mul_f32 v[18:19], v[6:7], v[8:9] op_sel:[0,1]
	v_addc_co_u32_e64 v15, s[2:3], 0, v13, s[2:3]
	global_store_dword v[16:17], v11, off offset:512
	s_waitcnt lgkmcnt(6)
	v_lshlrev_b32_e32 v12, 16, v25
	v_and_b32_e32 v13, 0xffff0000, v25
	v_cvt_pk_bf16_f32 v1, v8, v9
	v_pk_fma_f32 v[20:21], v[2:3], v[8:9], v[18:19] neg_lo:[0,0,1] neg_hi:[0,0,1]
	v_pk_fma_f32 v[8:9], v[2:3], v[8:9], v[18:19] op_sel_hi:[1,0,1]
	global_store_dword v[16:17], v1, off offset:1280
	v_mov_b32_e32 v21, v9
	v_pk_add_f32 v[8:9], v[20:21], v[12:13]
	s_waitcnt lgkmcnt(5)
	v_lshlrev_b32_e32 v18, 16, v26
	v_pk_mul_f32 v[12:13], v[6:7], v[8:9] op_sel:[0,1]
	v_cvt_pk_bf16_f32 v1, v8, v9
	v_pk_fma_f32 v[20:21], v[2:3], v[8:9], v[12:13] neg_lo:[0,0,1] neg_hi:[0,0,1]
	v_pk_fma_f32 v[8:9], v[2:3], v[8:9], v[12:13] op_sel_hi:[1,0,1]
	v_and_b32_e32 v19, 0xffff0000, v26
	v_mov_b32_e32 v21, v9
	v_pk_add_f32 v[8:9], v[20:21], v[18:19]
	global_store_dword v[16:17], v1, off offset:2048
	v_pk_mul_f32 v[12:13], v[6:7], v[8:9] op_sel:[0,1]
	v_cvt_pk_bf16_f32 v1, v8, v9
	v_pk_fma_f32 v[20:21], v[2:3], v[8:9], v[12:13] neg_lo:[0,0,1] neg_hi:[0,0,1]
	v_pk_fma_f32 v[8:9], v[2:3], v[8:9], v[12:13] op_sel_hi:[1,0,1]
	s_waitcnt lgkmcnt(4)
	v_lshlrev_b32_e32 v18, 16, v27
	v_and_b32_e32 v19, 0xffff0000, v27
	v_mov_b32_e32 v21, v9
	v_pk_add_f32 v[8:9], v[20:21], v[18:19]
	global_store_dword v[16:17], v1, off offset:2816
	v_pk_mul_f32 v[12:13], v[6:7], v[8:9] op_sel:[0,1]
	v_cvt_pk_bf16_f32 v1, v8, v9
	v_pk_fma_f32 v[18:19], v[2:3], v[8:9], v[12:13] neg_lo:[0,0,1] neg_hi:[0,0,1]
	v_pk_fma_f32 v[8:9], v[2:3], v[8:9], v[12:13] op_sel_hi:[1,0,1]
	global_store_dword v[16:17], v1, off offset:3584
	s_waitcnt lgkmcnt(3)
	v_lshlrev_b32_e32 v16, 16, v28
	v_and_b32_e32 v17, 0xffff0000, v28
	v_mov_b32_e32 v19, v9
	v_pk_add_f32 v[8:9], v[18:19], v[16:17]
	s_waitcnt lgkmcnt(2)
	v_lshlrev_b32_e32 v16, 16, v29
	v_pk_mul_f32 v[12:13], v[6:7], v[8:9] op_sel:[0,1]
	v_cvt_pk_bf16_f32 v1, v8, v9
	v_pk_fma_f32 v[18:19], v[2:3], v[8:9], v[12:13] neg_lo:[0,0,1] neg_hi:[0,0,1]
	v_pk_fma_f32 v[8:9], v[2:3], v[8:9], v[12:13] op_sel_hi:[1,0,1]
	v_and_b32_e32 v17, 0xffff0000, v29
	v_mov_b32_e32 v19, v9
	v_pk_add_f32 v[8:9], v[18:19], v[16:17]
	global_store_dword v[14:15], v1, off offset:256
	v_pk_mul_f32 v[12:13], v[6:7], v[8:9] op_sel:[0,1]
	v_cvt_pk_bf16_f32 v1, v8, v9
	v_pk_fma_f32 v[18:19], v[2:3], v[8:9], v[12:13] neg_lo:[0,0,1] neg_hi:[0,0,1]
	v_pk_fma_f32 v[8:9], v[2:3], v[8:9], v[12:13] op_sel_hi:[1,0,1]
	s_waitcnt lgkmcnt(1)
	v_lshlrev_b32_e32 v16, 16, v30
	v_and_b32_e32 v17, 0xffff0000, v30
	v_mov_b32_e32 v19, v9
	v_pk_add_f32 v[8:9], v[18:19], v[16:17]
	s_add_u32 s6, s6, 0x1800
	v_pk_mul_f32 v[12:13], v[6:7], v[8:9] op_sel:[0,1]
	global_store_dword v[14:15], v1, off offset:1024
	v_cvt_pk_bf16_f32 v1, v8, v9
	v_pk_fma_f32 v[16:17], v[2:3], v[8:9], v[12:13] neg_lo:[0,0,1] neg_hi:[0,0,1]
	v_pk_fma_f32 v[8:9], v[2:3], v[8:9], v[12:13] op_sel_hi:[1,0,1]
	s_addc_u32 s7, s7, 0
	global_store_dword v[14:15], v1, off offset:1792
	s_waitcnt lgkmcnt(0)
	v_lshlrev_b32_e32 v14, 16, v31
	v_and_b32_e32 v15, 0xffff0000, v31
	v_mov_b32_e32 v17, v9
	s_cmp_eq_u32 s6, 0x18000
	v_add_u32_e32 v10, 0x900, v10
	v_pk_add_f32 v[8:9], v[16:17], v[14:15]
	s_cbranch_scc0 .LBB0_456
